# hand-written retention EpiP: 96 distinct decay factors per lane (shared across ai==bj groups), packed f32 argument math, uniform sign off the diagonal
# speedup vs baseline: 1.0179x; 1.0012x over previous
; __device__ __forceinline__ float ex2(float x) { return __builtin_amdgcn_exp2f(x); }
; __device__ __forceinline__ u32x4 pack8(const f32x4 a, const f32x4 b) { u32x4 w; w.x = pk2(a[0], a[1]); w.y = pk2(a[2], a[3]); w.z = pk2(b[0], b[1]); w.w = pk2(b[2], b[3]); return w; }
;     __device__ __forceinline__ bool operator()(EPI_ARGS) const {
;         const int h = u.z; const float lgf = dec[h], lgb = dec[4 + h];
; #pragma unroll
;         for (int ai = 0; ai < 2; ++ai)
; #pragma unroll
;             for (int m = 0; m < 4; ++m) {
;                 const int il = ROWLOC(ai, m), i = u.pm * 256 + il;
; #pragma unroll
;                 for (int bj = 0; bj < 2; ++bj) {
;                     const int j0 = u.w * 256 + COLLOC(bj);
;                     f32x4 p[2];
; #pragma unroll
;                     for (int n = 0; n < 2; ++n)
; #pragma unroll
;                         for (int e = 0; e < 4; ++e) { const int d = i - (j0 + 4 * n + e); const float w = ex2(d >= 0 ? (float)d * lgf : (float)(-d) * lgb); p[n][e] = acc[ai][bj][m][n][e] * w; }
;                     *(u32x4*)(pscr + (size_t)il * D + j0) = pack8(p[0], p[1]);
;                 }
;             }
;         return false;
.LBB0_833:
	v_mov_b32_e32 v130, v145
	v_mov_b32_e32 v131, v146
	s_cmp_lt_i32 s35, 2
	s_cselect_b32 s58, s72, s58
	s_cselect_b32 s33, s50, s33
	s_cselect_b32 s34, s35, s34
	s_ashr_i32 s59, s58, 31
	s_lshl_b64 s[16:17], s[58:59], 2
	s_add_u32 s16, s4, s16
	s_addc_u32 s17, s5, s17
	global_load_dword v149, v129, s[16:17]
	global_load_dword v150, v129, s[16:17] offset:16
	s_lshl_b32 s17, s34, 8
	v_add_u32_e32 v138, s68, v130
	s_lshl_b32 s16, s33, 8
	s_or_b32 s17, s17, s64
	v_add_u32_e32 v153, s16, v138
	v_lshl_add_u32 v140, v131, 3, s17
	v_sub_u32_e32 v130, v153, v140
	v_cvt_f32_i32_e32 v178, v130
	v_lshlrev_b32_e32 v196, 11, v138
	v_lshl_add_u32 v196, v140, 1, v196
	s_nop 0
	v_add_f32_e32 v179, -1.0, v178
	v_add_f32_e32 v180, -2.0, v178
	v_add_f32_e32 v181, 0xc0400000, v178
	v_add_f32_e32 v182, -4.0, v178
	v_add_f32_e32 v183, 0xc0a00000, v178
	v_add_f32_e32 v184, 0xc0c00000, v178
	v_add_f32_e32 v185, 0xc0e00000, v178
	s_waitcnt vmcnt(0)
	v_readfirstlane_b32 s98, v149
	v_readfirstlane_b32 s100, v150
	s_xor_b32 s100, s100, 0x80000000
	s_cmp_ge_i32 s33, s34
	s_cselect_b32 s99, s98, s100
	s_cmp_gt_i32 s33, s34
	s_cselect_b32 s101, s98, s100
	v_mov_b32_e32 v158, s99
	v_mov_b32_e32 v160, s101
	v_mov_b32_e32 v162, s100
	v_mov_b32_e32 v197, v196
	v_add_u32_e32 v198, 0x40000, v196
	s_mov_b32 s16, 0x00000000
	v_pk_add_f32 v[186:187], v[178:179], s[16:17] op_sel_hi:[1,0]
	v_pk_add_f32 v[188:189], v[180:181], s[16:17] op_sel_hi:[1,0]
	v_pk_add_f32 v[190:191], v[182:183], s[16:17] op_sel_hi:[1,0]
	v_pk_add_f32 v[192:193], v[184:185], s[16:17] op_sel_hi:[1,0]
	v_cmp_gt_f32_e32 vcc, 0, v186
	s_nop 1
	v_cndmask_b32_e32 v194, v149, v162, vcc
	v_cmp_gt_f32_e32 vcc, 0, v187
	v_mul_f32_e32 v186, v186, v194
	s_nop 0
	v_cndmask_b32_e32 v195, v149, v162, vcc
	v_cmp_gt_f32_e32 vcc, 0, v188
	v_mul_f32_e32 v187, v187, v195
	s_nop 0
	v_cndmask_b32_e32 v194, v149, v162, vcc
	v_cmp_gt_f32_e32 vcc, 0, v189
	v_mul_f32_e32 v188, v188, v194
	s_nop 0
	v_cndmask_b32_e32 v195, v149, v162, vcc
	v_cmp_gt_f32_e32 vcc, 0, v190
	v_mul_f32_e32 v189, v189, v195
	s_nop 0
	v_cndmask_b32_e32 v194, v149, v162, vcc
	v_cmp_gt_f32_e32 vcc, 0, v191
	v_mul_f32_e32 v190, v190, v194
	s_nop 0
	v_cndmask_b32_e32 v195, v149, v162, vcc
	v_cmp_gt_f32_e32 vcc, 0, v192
	v_mul_f32_e32 v191, v191, v195
	s_nop 0
	v_cndmask_b32_e32 v194, v149, v162, vcc
	v_cmp_gt_f32_e32 vcc, 0, v193
	v_mul_f32_e32 v192, v192, v194
	s_nop 0
	v_cndmask_b32_e32 v195, v149, v162, vcc
	v_mul_f32_e32 v193, v193, v195
	v_exp_f32_e32 v186, v186
	v_exp_f32_e32 v187, v187
	v_exp_f32_e32 v188, v188
	v_exp_f32_e32 v189, v189
	v_exp_f32_e32 v190, v190
	v_exp_f32_e32 v191, v191
	v_exp_f32_e32 v192, v192
	v_exp_f32_e32 v193, v193
	v_pk_mul_f32 v[124:125], v[124:125], v[186:187]
	v_pk_mul_f32 v[126:127], v[126:127], v[188:189]
	v_pk_mul_f32 v[120:121], v[120:121], v[190:191]
	v_pk_mul_f32 v[122:123], v[122:123], v[192:193]
	v_cvt_pk_bf16_f32 v124, v124, v125
	v_cvt_pk_bf16_f32 v125, v126, v127
	v_cvt_pk_bf16_f32 v126, v120, v121
	v_cvt_pk_bf16_f32 v127, v122, v123
	global_store_dwordx4 v197, v[124:127], s[80:81]
	v_pk_mul_f32 v[52:53], v[52:53], v[186:187]
	v_pk_mul_f32 v[54:55], v[54:55], v[188:189]
	v_pk_mul_f32 v[48:49], v[48:49], v[190:191]
	v_pk_mul_f32 v[50:51], v[50:51], v[192:193]
	v_cvt_pk_bf16_f32 v52, v52, v53
	v_cvt_pk_bf16_f32 v53, v54, v55
	v_cvt_pk_bf16_f32 v54, v48, v49
	v_cvt_pk_bf16_f32 v55, v50, v51
	global_store_dwordx4 v198, v[52:55], s[80:81] offset:256
	s_mov_b32 s16, 0x43000000
	v_pk_add_f32 v[186:187], v[178:179], s[16:17] op_sel_hi:[1,0]
	v_pk_add_f32 v[188:189], v[180:181], s[16:17] op_sel_hi:[1,0]
	v_pk_add_f32 v[190:191], v[182:183], s[16:17] op_sel_hi:[1,0]
	v_pk_add_f32 v[192:193], v[184:185], s[16:17] op_sel_hi:[1,0]
	v_pk_mul_f32 v[186:187], v[186:187], v[158:159] op_sel_hi:[1,0]
	v_pk_mul_f32 v[188:189], v[188:189], v[158:159] op_sel_hi:[1,0]
	v_pk_mul_f32 v[190:191], v[190:191], v[158:159] op_sel_hi:[1,0]
	v_pk_mul_f32 v[192:193], v[192:193], v[158:159] op_sel_hi:[1,0]
	v_exp_f32_e32 v186, v186
	v_exp_f32_e32 v187, v187
	v_exp_f32_e32 v188, v188
	v_exp_f32_e32 v189, v189
	v_exp_f32_e32 v190, v190
	v_exp_f32_e32 v191, v191
	v_exp_f32_e32 v192, v192
	v_exp_f32_e32 v193, v193
	v_pk_mul_f32 v[60:61], v[60:61], v[186:187]
	v_pk_mul_f32 v[62:63], v[62:63], v[188:189]
	v_pk_mul_f32 v[56:57], v[56:57], v[190:191]
	v_pk_mul_f32 v[58:59], v[58:59], v[192:193]
	v_cvt_pk_bf16_f32 v60, v60, v61
	v_cvt_pk_bf16_f32 v61, v62, v63
	v_cvt_pk_bf16_f32 v62, v56, v57
	v_cvt_pk_bf16_f32 v63, v58, v59
	global_store_dwordx4 v198, v[60:63], s[80:81]
	s_mov_b32 s16, 0xc3000000
	v_pk_add_f32 v[186:187], v[178:179], s[16:17] op_sel_hi:[1,0]
	v_pk_add_f32 v[188:189], v[180:181], s[16:17] op_sel_hi:[1,0]
	v_pk_add_f32 v[190:191], v[182:183], s[16:17] op_sel_hi:[1,0]
	v_pk_add_f32 v[192:193], v[184:185], s[16:17] op_sel_hi:[1,0]
	v_pk_mul_f32 v[186:187], v[186:187], v[160:161] op_sel_hi:[1,0]
	v_pk_mul_f32 v[188:189], v[188:189], v[160:161] op_sel_hi:[1,0]
	v_pk_mul_f32 v[190:191], v[190:191], v[160:161] op_sel_hi:[1,0]
	v_pk_mul_f32 v[192:193], v[192:193], v[160:161] op_sel_hi:[1,0]
	v_exp_f32_e32 v186, v186
	v_exp_f32_e32 v187, v187
	v_exp_f32_e32 v188, v188
	v_exp_f32_e32 v189, v189
	v_exp_f32_e32 v190, v190
	v_exp_f32_e32 v191, v191
	v_exp_f32_e32 v192, v192
	v_exp_f32_e32 v193, v193
	v_pk_mul_f32 v[116:117], v[116:117], v[186:187]
	v_pk_mul_f32 v[118:119], v[118:119], v[188:189]
	v_pk_mul_f32 v[112:113], v[112:113], v[190:191]
	v_pk_mul_f32 v[114:115], v[114:115], v[192:193]
	v_cvt_pk_bf16_f32 v116, v116, v117
	v_cvt_pk_bf16_f32 v117, v118, v119
	v_cvt_pk_bf16_f32 v118, v112, v113
	v_cvt_pk_bf16_f32 v119, v114, v115
; __device__ __forceinline__ float ex2(float x) { return __builtin_amdgcn_exp2f(x); }
; __device__ __forceinline__ u32x4 pack8(const f32x4 a, const f32x4 b) { u32x4 w; w.x = pk2(a[0], a[1]); w.y = pk2(a[2], a[3]); w.z = pk2(b[0], b[1]); w.w = pk2(b[2], b[3]); return w; }
;     __device__ __forceinline__ bool operator()(EPI_ARGS) const {
;     ...
;         for (int ai = 0; ai < 2; ++ai)
; #pragma unroll
;             for (int m = 0; m < 4; ++m) {
;                 const int il = ROWLOC(ai, m), i = u.pm * 256 + il;
; #pragma unroll
;                 for (int bj = 0; bj < 2; ++bj) {
;                     const int j0 = u.w * 256 + COLLOC(bj);
;                     f32x4 p[2];
; #pragma unroll
;                     for (int n = 0; n < 2; ++n)
; #pragma unroll
;                         for (int e = 0; e < 4; ++e) { const int d = i - (j0 + 4 * n + e); const float w = ex2(d >= 0 ? (float)d * lgf : (float)(-d) * lgb); p[n][e] = acc[ai][bj][m][n][e] * w; }
;                     *(u32x4*)(pscr + (size_t)il * D + j0) = pack8(p[0], p[1]);
;                 }
	global_store_dwordx4 v197, v[116:119], s[80:81] offset:256
	v_add_u32_e32 v199, 0x8000, v196
	v_add_u32_e32 v200, 0x48000, v196
	s_mov_b32 s16, 0x41800000
	v_pk_add_f32 v[186:187], v[178:179], s[16:17] op_sel_hi:[1,0]
	v_pk_add_f32 v[188:189], v[180:181], s[16:17] op_sel_hi:[1,0]
	v_pk_add_f32 v[190:191], v[182:183], s[16:17] op_sel_hi:[1,0]
	v_pk_add_f32 v[192:193], v[184:185], s[16:17] op_sel_hi:[1,0]
	v_cmp_gt_f32_e32 vcc, 0, v186
	s_nop 1
	v_cndmask_b32_e32 v194, v149, v162, vcc
	v_cmp_gt_f32_e32 vcc, 0, v187
	v_mul_f32_e32 v186, v186, v194
	s_nop 0
	v_cndmask_b32_e32 v195, v149, v162, vcc
	v_cmp_gt_f32_e32 vcc, 0, v188
	v_mul_f32_e32 v187, v187, v195
	s_nop 0
	v_cndmask_b32_e32 v194, v149, v162, vcc
	v_cmp_gt_f32_e32 vcc, 0, v189
	v_mul_f32_e32 v188, v188, v194
	s_nop 0
	v_cndmask_b32_e32 v195, v149, v162, vcc
	v_cmp_gt_f32_e32 vcc, 0, v190
	v_mul_f32_e32 v189, v189, v195
	s_nop 0
	v_cndmask_b32_e32 v194, v149, v162, vcc
	v_cmp_gt_f32_e32 vcc, 0, v191
	v_mul_f32_e32 v190, v190, v194
	s_nop 0
	v_cndmask_b32_e32 v195, v149, v162, vcc
	v_cmp_gt_f32_e32 vcc, 0, v192
	v_mul_f32_e32 v191, v191, v195
	s_nop 0
	v_cndmask_b32_e32 v194, v149, v162, vcc
	v_cmp_gt_f32_e32 vcc, 0, v193
	v_mul_f32_e32 v192, v192, v194
	s_nop 0
	v_cndmask_b32_e32 v195, v149, v162, vcc
	v_mul_f32_e32 v193, v193, v195
	v_exp_f32_e32 v186, v186
	v_exp_f32_e32 v187, v187
	v_exp_f32_e32 v188, v188
	v_exp_f32_e32 v189, v189
	v_exp_f32_e32 v190, v190
	v_exp_f32_e32 v191, v191
	v_exp_f32_e32 v192, v192
	v_exp_f32_e32 v193, v193
	v_pk_mul_f32 v[108:109], v[108:109], v[186:187]
	v_pk_mul_f32 v[110:111], v[110:111], v[188:189]
	v_pk_mul_f32 v[104:105], v[104:105], v[190:191]
	v_pk_mul_f32 v[106:107], v[106:107], v[192:193]
	v_cvt_pk_bf16_f32 v108, v108, v109
	v_cvt_pk_bf16_f32 v109, v110, v111
	v_cvt_pk_bf16_f32 v110, v104, v105
	v_cvt_pk_bf16_f32 v111, v106, v107
	global_store_dwordx4 v199, v[108:111], s[80:81]
	v_pk_mul_f32 v[36:37], v[36:37], v[186:187]
	v_pk_mul_f32 v[38:39], v[38:39], v[188:189]
	v_pk_mul_f32 v[32:33], v[32:33], v[190:191]
	v_pk_mul_f32 v[34:35], v[34:35], v[192:193]
	v_cvt_pk_bf16_f32 v36, v36, v37
	v_cvt_pk_bf16_f32 v37, v38, v39
	v_cvt_pk_bf16_f32 v38, v32, v33
	v_cvt_pk_bf16_f32 v39, v34, v35
	global_store_dwordx4 v200, v[36:39], s[80:81] offset:256
	s_mov_b32 s16, 0x43100000
	v_pk_add_f32 v[186:187], v[178:179], s[16:17] op_sel_hi:[1,0]
	v_pk_add_f32 v[188:189], v[180:181], s[16:17] op_sel_hi:[1,0]
	v_pk_add_f32 v[190:191], v[182:183], s[16:17] op_sel_hi:[1,0]
	v_pk_add_f32 v[192:193], v[184:185], s[16:17] op_sel_hi:[1,0]
	v_pk_mul_f32 v[186:187], v[186:187], v[158:159] op_sel_hi:[1,0]
	v_pk_mul_f32 v[188:189], v[188:189], v[158:159] op_sel_hi:[1,0]
	v_pk_mul_f32 v[190:191], v[190:191], v[158:159] op_sel_hi:[1,0]
	v_pk_mul_f32 v[192:193], v[192:193], v[158:159] op_sel_hi:[1,0]
	v_exp_f32_e32 v186, v186
	v_exp_f32_e32 v187, v187
	v_exp_f32_e32 v188, v188
	v_exp_f32_e32 v189, v189
	v_exp_f32_e32 v190, v190
	v_exp_f32_e32 v191, v191
	v_exp_f32_e32 v192, v192
	v_exp_f32_e32 v193, v193
	v_pk_mul_f32 v[44:45], v[44:45], v[186:187]
	v_pk_mul_f32 v[46:47], v[46:47], v[188:189]
	v_pk_mul_f32 v[40:41], v[40:41], v[190:191]
	v_pk_mul_f32 v[42:43], v[42:43], v[192:193]
	v_cvt_pk_bf16_f32 v44, v44, v45
	v_cvt_pk_bf16_f32 v45, v46, v47
	v_cvt_pk_bf16_f32 v46, v40, v41
	v_cvt_pk_bf16_f32 v47, v42, v43
	global_store_dwordx4 v200, v[44:47], s[80:81]
	s_mov_b32 s16, 0xc2e00000
	v_pk_add_f32 v[186:187], v[178:179], s[16:17] op_sel_hi:[1,0]
	v_pk_add_f32 v[188:189], v[180:181], s[16:17] op_sel_hi:[1,0]
	v_pk_add_f32 v[190:191], v[182:183], s[16:17] op_sel_hi:[1,0]
	v_pk_add_f32 v[192:193], v[184:185], s[16:17] op_sel_hi:[1,0]
	v_pk_mul_f32 v[186:187], v[186:187], v[160:161] op_sel_hi:[1,0]
	v_pk_mul_f32 v[188:189], v[188:189], v[160:161] op_sel_hi:[1,0]
	v_pk_mul_f32 v[190:191], v[190:191], v[160:161] op_sel_hi:[1,0]
	v_pk_mul_f32 v[192:193], v[192:193], v[160:161] op_sel_hi:[1,0]
	v_exp_f32_e32 v186, v186
	v_exp_f32_e32 v187, v187
	v_exp_f32_e32 v188, v188
	v_exp_f32_e32 v189, v189
	v_exp_f32_e32 v190, v190
	v_exp_f32_e32 v191, v191
	v_exp_f32_e32 v192, v192
	v_exp_f32_e32 v193, v193
	v_pk_mul_f32 v[100:101], v[100:101], v[186:187]
	v_pk_mul_f32 v[102:103], v[102:103], v[188:189]
	v_pk_mul_f32 v[96:97], v[96:97], v[190:191]
	v_pk_mul_f32 v[98:99], v[98:99], v[192:193]
	v_cvt_pk_bf16_f32 v100, v100, v101
	v_cvt_pk_bf16_f32 v101, v102, v103
	v_cvt_pk_bf16_f32 v102, v96, v97
	v_cvt_pk_bf16_f32 v103, v98, v99
	global_store_dwordx4 v199, v[100:103], s[80:81] offset:256
	v_add_u32_e32 v201, 0x10000, v196
	v_add_u32_e32 v202, 0x50000, v196
	s_mov_b32 s16, 0x42000000
	v_pk_add_f32 v[186:187], v[178:179], s[16:17] op_sel_hi:[1,0]
	v_pk_add_f32 v[188:189], v[180:181], s[16:17] op_sel_hi:[1,0]
	v_pk_add_f32 v[190:191], v[182:183], s[16:17] op_sel_hi:[1,0]
	v_pk_add_f32 v[192:193], v[184:185], s[16:17] op_sel_hi:[1,0]
	v_cmp_gt_f32_e32 vcc, 0, v186
	s_nop 1
	v_cndmask_b32_e32 v194, v149, v162, vcc
	v_cmp_gt_f32_e32 vcc, 0, v187
	v_mul_f32_e32 v186, v186, v194
	s_nop 0
	v_cndmask_b32_e32 v195, v149, v162, vcc
	v_cmp_gt_f32_e32 vcc, 0, v188
	v_mul_f32_e32 v187, v187, v195
	s_nop 0
	v_cndmask_b32_e32 v194, v149, v162, vcc
	v_cmp_gt_f32_e32 vcc, 0, v189
	v_mul_f32_e32 v188, v188, v194
	s_nop 0
	v_cndmask_b32_e32 v195, v149, v162, vcc
	v_cmp_gt_f32_e32 vcc, 0, v190
	v_mul_f32_e32 v189, v189, v195
	s_nop 0
	v_cndmask_b32_e32 v194, v149, v162, vcc
	v_cmp_gt_f32_e32 vcc, 0, v191
	v_mul_f32_e32 v190, v190, v194
	s_nop 0
	v_cndmask_b32_e32 v195, v149, v162, vcc
	v_cmp_gt_f32_e32 vcc, 0, v192
	v_mul_f32_e32 v191, v191, v195
	s_nop 0
	v_cndmask_b32_e32 v194, v149, v162, vcc
; __device__ __forceinline__ float ex2(float x) { return __builtin_amdgcn_exp2f(x); }
; __device__ __forceinline__ u32x4 pack8(const f32x4 a, const f32x4 b) { u32x4 w; w.x = pk2(a[0], a[1]); w.y = pk2(a[2], a[3]); w.z = pk2(b[0], b[1]); w.w = pk2(b[2], b[3]); return w; }
;     __device__ __forceinline__ bool operator()(EPI_ARGS) const {
;     ...
;         for (int ai = 0; ai < 2; ++ai)
; #pragma unroll
;             for (int m = 0; m < 4; ++m) {
;                 const int il = ROWLOC(ai, m), i = u.pm * 256 + il;
; #pragma unroll
;                 for (int bj = 0; bj < 2; ++bj) {
;                     const int j0 = u.w * 256 + COLLOC(bj);
;                     f32x4 p[2];
; #pragma unroll
;                     for (int n = 0; n < 2; ++n)
; #pragma unroll
;                         for (int e = 0; e < 4; ++e) { const int d = i - (j0 + 4 * n + e); const float w = ex2(d >= 0 ? (float)d * lgf : (float)(-d) * lgb); p[n][e] = acc[ai][bj][m][n][e] * w; }
;                     *(u32x4*)(pscr + (size_t)il * D + j0) = pack8(p[0], p[1]);
;                 }
	v_cmp_gt_f32_e32 vcc, 0, v193
	v_mul_f32_e32 v192, v192, v194
	s_nop 0
	v_cndmask_b32_e32 v195, v149, v162, vcc
	v_mul_f32_e32 v193, v193, v195
	v_exp_f32_e32 v186, v186
	v_exp_f32_e32 v187, v187
	v_exp_f32_e32 v188, v188
	v_exp_f32_e32 v189, v189
	v_exp_f32_e32 v190, v190
	v_exp_f32_e32 v191, v191
	v_exp_f32_e32 v192, v192
	v_exp_f32_e32 v193, v193
	v_pk_mul_f32 v[92:93], v[92:93], v[186:187]
	v_pk_mul_f32 v[94:95], v[94:95], v[188:189]
	v_pk_mul_f32 v[88:89], v[88:89], v[190:191]
	v_pk_mul_f32 v[90:91], v[90:91], v[192:193]
	v_cvt_pk_bf16_f32 v92, v92, v93
	v_cvt_pk_bf16_f32 v93, v94, v95
	v_cvt_pk_bf16_f32 v94, v88, v89
	v_cvt_pk_bf16_f32 v95, v90, v91
	global_store_dwordx4 v201, v[92:95], s[80:81]
	v_pk_mul_f32 v[20:21], v[20:21], v[186:187]
	v_pk_mul_f32 v[22:23], v[22:23], v[188:189]
	v_pk_mul_f32 v[16:17], v[16:17], v[190:191]
	v_pk_mul_f32 v[18:19], v[18:19], v[192:193]
	v_cvt_pk_bf16_f32 v20, v20, v21
	v_cvt_pk_bf16_f32 v21, v22, v23
	v_cvt_pk_bf16_f32 v22, v16, v17
	v_cvt_pk_bf16_f32 v23, v18, v19
	global_store_dwordx4 v202, v[20:23], s[80:81] offset:256
	s_mov_b32 s16, 0x43200000
	v_pk_add_f32 v[186:187], v[178:179], s[16:17] op_sel_hi:[1,0]
	v_pk_add_f32 v[188:189], v[180:181], s[16:17] op_sel_hi:[1,0]
	v_pk_add_f32 v[190:191], v[182:183], s[16:17] op_sel_hi:[1,0]
	v_pk_add_f32 v[192:193], v[184:185], s[16:17] op_sel_hi:[1,0]
	v_pk_mul_f32 v[186:187], v[186:187], v[158:159] op_sel_hi:[1,0]
	v_pk_mul_f32 v[188:189], v[188:189], v[158:159] op_sel_hi:[1,0]
	v_pk_mul_f32 v[190:191], v[190:191], v[158:159] op_sel_hi:[1,0]
	v_pk_mul_f32 v[192:193], v[192:193], v[158:159] op_sel_hi:[1,0]
	v_exp_f32_e32 v186, v186
	v_exp_f32_e32 v187, v187
	v_exp_f32_e32 v188, v188
	v_exp_f32_e32 v189, v189
	v_exp_f32_e32 v190, v190
	v_exp_f32_e32 v191, v191
	v_exp_f32_e32 v192, v192
	v_exp_f32_e32 v193, v193
	v_pk_mul_f32 v[28:29], v[28:29], v[186:187]
	v_pk_mul_f32 v[30:31], v[30:31], v[188:189]
	v_pk_mul_f32 v[24:25], v[24:25], v[190:191]
	v_pk_mul_f32 v[26:27], v[26:27], v[192:193]
	v_cvt_pk_bf16_f32 v28, v28, v29
	v_cvt_pk_bf16_f32 v29, v30, v31
	v_cvt_pk_bf16_f32 v30, v24, v25
	v_cvt_pk_bf16_f32 v31, v26, v27
	global_store_dwordx4 v202, v[28:31], s[80:81]
	s_mov_b32 s16, 0xc2c00000
	v_pk_add_f32 v[186:187], v[178:179], s[16:17] op_sel_hi:[1,0]
	v_pk_add_f32 v[188:189], v[180:181], s[16:17] op_sel_hi:[1,0]
	v_pk_add_f32 v[190:191], v[182:183], s[16:17] op_sel_hi:[1,0]
	v_pk_add_f32 v[192:193], v[184:185], s[16:17] op_sel_hi:[1,0]
	v_pk_mul_f32 v[186:187], v[186:187], v[160:161] op_sel_hi:[1,0]
	v_pk_mul_f32 v[188:189], v[188:189], v[160:161] op_sel_hi:[1,0]
	v_pk_mul_f32 v[190:191], v[190:191], v[160:161] op_sel_hi:[1,0]
	v_pk_mul_f32 v[192:193], v[192:193], v[160:161] op_sel_hi:[1,0]
	v_exp_f32_e32 v186, v186
	v_exp_f32_e32 v187, v187
	v_exp_f32_e32 v188, v188
	v_exp_f32_e32 v189, v189
	v_exp_f32_e32 v190, v190
	v_exp_f32_e32 v191, v191
	v_exp_f32_e32 v192, v192
	v_exp_f32_e32 v193, v193
	v_pk_mul_f32 v[84:85], v[84:85], v[186:187]
	v_pk_mul_f32 v[86:87], v[86:87], v[188:189]
	v_pk_mul_f32 v[80:81], v[80:81], v[190:191]
	v_pk_mul_f32 v[82:83], v[82:83], v[192:193]
	v_cvt_pk_bf16_f32 v84, v84, v85
	v_cvt_pk_bf16_f32 v85, v86, v87
	v_cvt_pk_bf16_f32 v86, v80, v81
	v_cvt_pk_bf16_f32 v87, v82, v83
	global_store_dwordx4 v201, v[84:87], s[80:81] offset:256
	v_add_u32_e32 v203, 0x18000, v196
	v_add_u32_e32 v204, 0x58000, v196
	s_mov_b32 s16, 0x42400000
	v_pk_add_f32 v[186:187], v[178:179], s[16:17] op_sel_hi:[1,0]
	v_pk_add_f32 v[188:189], v[180:181], s[16:17] op_sel_hi:[1,0]
	v_pk_add_f32 v[190:191], v[182:183], s[16:17] op_sel_hi:[1,0]
	v_pk_add_f32 v[192:193], v[184:185], s[16:17] op_sel_hi:[1,0]
	v_cmp_gt_f32_e32 vcc, 0, v186
	s_nop 1
	v_cndmask_b32_e32 v194, v149, v162, vcc
	v_cmp_gt_f32_e32 vcc, 0, v187
	v_mul_f32_e32 v186, v186, v194
	s_nop 0
	v_cndmask_b32_e32 v195, v149, v162, vcc
	v_cmp_gt_f32_e32 vcc, 0, v188
	v_mul_f32_e32 v187, v187, v195
	s_nop 0
; __device__ __forceinline__ float ex2(float x) { return __builtin_amdgcn_exp2f(x); }
; __device__ __forceinline__ u32x4 pack8(const f32x4 a, const f32x4 b) { u32x4 w; w.x = pk2(a[0], a[1]); w.y = pk2(a[2], a[3]); w.z = pk2(b[0], b[1]); w.w = pk2(b[2], b[3]); return w; }
;     __device__ __forceinline__ bool operator()(EPI_ARGS) const {
;     ...
;         for (int ai = 0; ai < 2; ++ai)
; #pragma unroll
;             for (int m = 0; m < 4; ++m) {
;                 const int il = ROWLOC(ai, m), i = u.pm * 256 + il;
; #pragma unroll
;                 for (int bj = 0; bj < 2; ++bj) {
;                     const int j0 = u.w * 256 + COLLOC(bj);
;                     f32x4 p[2];
; #pragma unroll
;                     for (int n = 0; n < 2; ++n)
; #pragma unroll
;                         for (int e = 0; e < 4; ++e) { const int d = i - (j0 + 4 * n + e); const float w = ex2(d >= 0 ? (float)d * lgf : (float)(-d) * lgb); p[n][e] = acc[ai][bj][m][n][e] * w; }
;                     *(u32x4*)(pscr + (size_t)il * D + j0) = pack8(p[0], p[1]);
;                 }
	v_cndmask_b32_e32 v194, v149, v162, vcc
	v_cmp_gt_f32_e32 vcc, 0, v189
	v_mul_f32_e32 v188, v188, v194
	s_nop 0
	v_cndmask_b32_e32 v195, v149, v162, vcc
	v_cmp_gt_f32_e32 vcc, 0, v190
	v_mul_f32_e32 v189, v189, v195
	s_nop 0
	v_cndmask_b32_e32 v194, v149, v162, vcc
	v_cmp_gt_f32_e32 vcc, 0, v191
	v_mul_f32_e32 v190, v190, v194
	s_nop 0
	v_cndmask_b32_e32 v195, v149, v162, vcc
	v_cmp_gt_f32_e32 vcc, 0, v192
	v_mul_f32_e32 v191, v191, v195
	s_nop 0
	v_cndmask_b32_e32 v194, v149, v162, vcc
	v_cmp_gt_f32_e32 vcc, 0, v193
	v_mul_f32_e32 v192, v192, v194
	s_nop 0
	v_cndmask_b32_e32 v195, v149, v162, vcc
	v_mul_f32_e32 v193, v193, v195
	v_exp_f32_e32 v186, v186
	v_exp_f32_e32 v187, v187
	v_exp_f32_e32 v188, v188
	v_exp_f32_e32 v189, v189
	v_exp_f32_e32 v190, v190
	v_exp_f32_e32 v191, v191
	v_exp_f32_e32 v192, v192
	v_exp_f32_e32 v193, v193
	v_pk_mul_f32 v[76:77], v[76:77], v[186:187]
	v_pk_mul_f32 v[78:79], v[78:79], v[188:189]
	v_pk_mul_f32 v[72:73], v[72:73], v[190:191]
	v_pk_mul_f32 v[74:75], v[74:75], v[192:193]
	v_cvt_pk_bf16_f32 v76, v76, v77
	v_cvt_pk_bf16_f32 v77, v78, v79
	v_cvt_pk_bf16_f32 v78, v72, v73
	v_cvt_pk_bf16_f32 v79, v74, v75
	global_store_dwordx4 v203, v[76:79], s[80:81]
	v_pk_mul_f32 v[4:5], v[4:5], v[186:187]
	v_pk_mul_f32 v[6:7], v[6:7], v[188:189]
	v_pk_mul_f32 v[0:1], v[0:1], v[190:191]
	v_pk_mul_f32 v[2:3], v[2:3], v[192:193]
	v_cvt_pk_bf16_f32 v4, v4, v5
	v_cvt_pk_bf16_f32 v5, v6, v7
	v_cvt_pk_bf16_f32 v6, v0, v1
	v_cvt_pk_bf16_f32 v7, v2, v3
	global_store_dwordx4 v204, v[4:7], s[80:81] offset:256
	s_mov_b32 s16, 0x43300000
	v_pk_add_f32 v[186:187], v[178:179], s[16:17] op_sel_hi:[1,0]
	v_pk_add_f32 v[188:189], v[180:181], s[16:17] op_sel_hi:[1,0]
	v_pk_add_f32 v[190:191], v[182:183], s[16:17] op_sel_hi:[1,0]
	v_pk_add_f32 v[192:193], v[184:185], s[16:17] op_sel_hi:[1,0]
	v_pk_mul_f32 v[186:187], v[186:187], v[158:159] op_sel_hi:[1,0]
	v_pk_mul_f32 v[188:189], v[188:189], v[158:159] op_sel_hi:[1,0]
	v_pk_mul_f32 v[190:191], v[190:191], v[158:159] op_sel_hi:[1,0]
	v_pk_mul_f32 v[192:193], v[192:193], v[158:159] op_sel_hi:[1,0]
	v_exp_f32_e32 v186, v186
	v_exp_f32_e32 v187, v187
	v_exp_f32_e32 v188, v188
	v_exp_f32_e32 v189, v189
	v_exp_f32_e32 v190, v190
	v_exp_f32_e32 v191, v191
	v_exp_f32_e32 v192, v192
	v_exp_f32_e32 v193, v193
	v_pk_mul_f32 v[12:13], v[12:13], v[186:187]
	v_pk_mul_f32 v[14:15], v[14:15], v[188:189]
	v_pk_mul_f32 v[8:9], v[8:9], v[190:191]
	v_pk_mul_f32 v[10:11], v[10:11], v[192:193]
	v_cvt_pk_bf16_f32 v12, v12, v13
	v_cvt_pk_bf16_f32 v13, v14, v15
	v_cvt_pk_bf16_f32 v14, v8, v9
	v_cvt_pk_bf16_f32 v15, v10, v11
	global_store_dwordx4 v204, v[12:15], s[80:81]
	s_mov_b32 s16, 0xc2a00000
	v_pk_add_f32 v[186:187], v[178:179], s[16:17] op_sel_hi:[1,0]
	v_pk_add_f32 v[188:189], v[180:181], s[16:17] op_sel_hi:[1,0]
	v_pk_add_f32 v[190:191], v[182:183], s[16:17] op_sel_hi:[1,0]
	v_pk_add_f32 v[192:193], v[184:185], s[16:17] op_sel_hi:[1,0]
	v_pk_mul_f32 v[186:187], v[186:187], v[160:161] op_sel_hi:[1,0]
	v_pk_mul_f32 v[188:189], v[188:189], v[160:161] op_sel_hi:[1,0]
	v_pk_mul_f32 v[190:191], v[190:191], v[160:161] op_sel_hi:[1,0]
	v_pk_mul_f32 v[192:193], v[192:193], v[160:161] op_sel_hi:[1,0]
	v_exp_f32_e32 v186, v186
	v_exp_f32_e32 v187, v187
	v_exp_f32_e32 v188, v188
	v_exp_f32_e32 v189, v189
	v_exp_f32_e32 v190, v190
	v_exp_f32_e32 v191, v191
	v_exp_f32_e32 v192, v192
	v_exp_f32_e32 v193, v193
	v_pk_mul_f32 v[68:69], v[68:69], v[186:187]
	v_pk_mul_f32 v[70:71], v[70:71], v[188:189]
	v_pk_mul_f32 v[64:65], v[64:65], v[190:191]
	v_pk_mul_f32 v[66:67], v[66:67], v[192:193]
	v_cvt_pk_bf16_f32 v68, v68, v69
	v_cvt_pk_bf16_f32 v69, v70, v71
	v_cvt_pk_bf16_f32 v70, v64, v65
	v_cvt_pk_bf16_f32 v71, v66, v67
	global_store_dwordx4 v203, v[68:71], s[80:81] offset:256
	s_mov_b64 s[16:17], -1
	s_andn2_b64 vcc, exec, s[6:7]
	s_cbranch_vccnz .LBB0_830
	s_andn2_b64 vcc, exec, s[78:79]
	s_cbranch_vccnz .LBB0_829
	s_barrier
	s_branch .LBB0_829
